# LN2 output section: 16 gain/bias/modulation vector loads batched ahead of the row reductions instead of 20 dependent round trips; on top of e2
# speedup vs baseline: 1.0094x; 1.0094x over previous
; __device__ __forceinline__ void ph_ln2(const Ctx& X, CArgs a, int l, int nrows) {
;     ...
;         float s[2] = {0.f, 0.f}, mean[2], rstd[2];
; #pragma unroll
;         for (int q = 0; q < 2; ++q)
; #pragma unroll
;             for (int j = 0; j < 4; ++j) { const int c = 4 * X.lane + 256 * j;
;                 v[q][j] = v[q][j] * DN_ALPHA + *(const f32x4*)(md + 5120 + c) * mo[q][j];
;                 s[q] += (v[q][j][0] + v[q][j][1]) + (v[q][j][2] + v[q][j][3]); }
; #pragma unroll
;         for (int q = 0; q < 2; ++q) mean[q] = wave_sum(s[q]) * (1.0f / D);
; #pragma unroll
;         for (int q = 0; q < 2; ++q) { float qq = 0.f;
; #pragma unroll
;             for (int j = 0; j < 4; ++j) { v[q][j] = v[q][j] - mean[q]; qq += (v[q][j][0] * v[q][j][0] + v[q][j][1] * v[q][j][1]) + (v[q][j][2] * v[q][j][2] + v[q][j][3] * v[q][j][3]); }
;             s[q] = qq; }
; #pragma unroll
;         for (int q = 0; q < 2; ++q) rstd[q] = 1.0f / sqrtf(wave_sum(s[q]) * (1.0f / D) + LN_EPS);
.LBB0_2347:
	s_min_i32 s6, s8, 0x8000
	s_ashr_i32 s6, s6, 13
	s_add_i32 s6, s6, s37
	s_mul_hi_i32 s7, s6, 0x6000
	s_mulk_i32 s6, 0x6000
	s_add_u32 s6, s2, s6
	s_addc_u32 s7, s3, s7
	v_lshlrev_b32_e32 v0, 2, v66
	v_lshl_add_u64 v[140:141], s[6:7], 0, v[0:1]
	s_mov_b64 s[6:7], 0x15000
	v_lshl_add_u64 v[148:149], v[140:141], 0, s[6:7]
	s_mov_b32 s6, 0x15000
	v_add_co_u32_e32 v140, vcc, s6, v140
	s_mov_b32 s6, 0x3fb504f3
	s_nop 0
	v_addc_co_u32_e32 v141, vcc, 0, v141, vcc
	global_load_dwordx4 v[140:143], v[140:141], off
	v_readlane_b32 s22, v254, 57
	global_load_dwordx4 v[144:147], v[148:149], off offset:2048
	v_readlane_b32 s23, v254, 58
	s_mov_b64 s[18:19], -1
	s_waitcnt vmcnt(1)
	v_pk_mul_f32 v[116:117], v[116:117], v[142:143]
	v_pk_mul_f32 v[118:119], v[118:119], v[140:141]
	v_pk_fma_f32 v[116:117], v[64:65], s[6:7], v[116:117] op_sel_hi:[1,0,1]
	v_pk_fma_f32 v[118:119], v[62:63], s[6:7], v[118:119] op_sel_hi:[1,0,1]
	v_mov_b32_e32 v65, v117
	v_pk_mov_b32 v[62:63], v[118:119], v[116:117] op_sel:[1,0]
	v_mov_b32_e32 v64, v118
	v_pk_add_f32 v[62:63], v[62:63], v[64:65]
	v_pk_mul_f32 v[122:123], v[122:123], v[142:143]
	v_add_f32_e32 v62, v62, v63
	v_add_f32_e32 v150, 0, v62
	global_load_dwordx4 v[62:65], v[148:149], off offset:1024
	s_waitcnt vmcnt(0)
	v_pk_mul_f32 v[108:109], v[108:109], v[64:65]
	v_pk_mul_f32 v[110:111], v[110:111], v[62:63]
	v_pk_fma_f32 v[108:109], v[60:61], s[6:7], v[108:109] op_sel_hi:[1,0,1]
	v_pk_fma_f32 v[110:111], v[58:59], s[6:7], v[110:111] op_sel_hi:[1,0,1]
	v_mov_b32_e32 v61, v109
	v_pk_mov_b32 v[58:59], v[110:111], v[108:109] op_sel:[1,0]
	v_mov_b32_e32 v60, v110
	v_pk_add_f32 v[58:59], v[58:59], v[60:61]
	v_pk_mul_f32 v[60:61], v[138:139], v[144:145]
	v_pk_add_f32 v[152:153], v[58:59], v[58:59] op_sel:[0,1] op_sel_hi:[1,0]
	v_pk_mul_f32 v[58:59], v[136:137], v[146:147]
	v_pk_fma_f32 v[60:61], v[54:55], s[6:7], v[60:61] op_sel_hi:[1,0,1]
	v_pk_fma_f32 v[58:59], v[56:57], s[6:7], v[58:59] op_sel_hi:[1,0,1]
	global_load_dwordx4 v[54:57], v[148:149], off offset:3072
	v_add_f32_e32 v136, v60, v61
	v_add_f32_e32 v138, v58, v59
	s_waitcnt vmcnt(0)
	v_pk_mul_f32 v[132:133], v[132:133], v[56:57]
	v_pk_mul_f32 v[134:135], v[134:135], v[54:55]
	v_pk_fma_f32 v[52:53], v[52:53], s[6:7], v[132:133] op_sel_hi:[1,0,1]
	v_pk_fma_f32 v[50:51], v[50:51], s[6:7], v[134:135] op_sel_hi:[1,0,1]
	v_mov_b32_e32 v137, v52
	v_mov_b32_e32 v151, v50
	v_mov_b32_e32 v153, v51
	v_mov_b32_e32 v139, v53
	v_pk_add_f32 v[132:133], v[150:151], v[152:153]
	v_pk_add_f32 v[134:135], v[136:137], v[138:139]
	s_nop 0
	v_pk_add_f32 v[132:133], v[132:133], v[134:135]
	s_nop 0
	v_add_f32_e32 v67, v132, v133
	v_pk_mul_f32 v[132:133], v[120:121], v[140:141]
	v_pk_fma_f32 v[120:121], v[48:49], s[6:7], v[122:123] op_sel_hi:[1,0,1]
	v_pk_fma_f32 v[122:123], v[46:47], s[6:7], v[132:133] op_sel_hi:[1,0,1]
	v_mov_b32_e32 v49, v121
	v_pk_mov_b32 v[46:47], v[122:123], v[120:121] op_sel:[1,0]
	v_mov_b32_e32 v48, v122
	v_pk_add_f32 v[46:47], v[46:47], v[48:49]
	v_pk_mul_f32 v[48:49], v[112:113], v[62:63]
	v_add_f32_e32 v46, v46, v47
	v_add_f32_e32 v132, 0, v46
	v_pk_mul_f32 v[46:47], v[114:115], v[64:65]
	v_pk_fma_f32 v[114:115], v[42:43], s[6:7], v[48:49] op_sel_hi:[1,0,1]
	v_pk_fma_f32 v[112:113], v[44:45], s[6:7], v[46:47] op_sel_hi:[1,0,1]
	v_mov_b32_e32 v44, v114
	v_pk_mov_b32 v[42:43], v[114:115], v[112:113] op_sel:[1,0]
	v_mov_b32_e32 v45, v113
	v_pk_add_f32 v[42:43], v[42:43], v[44:45]
	v_pk_mul_f32 v[44:45], v[130:131], v[146:147]
	v_pk_mul_f32 v[46:47], v[128:129], v[144:145]
	v_pk_fma_f32 v[62:63], v[40:41], s[6:7], v[44:45] op_sel_hi:[1,0,1]
	v_pk_mul_f32 v[44:45], v[126:127], v[56:57]
	v_pk_mul_f32 v[48:49], v[124:125], v[54:55]
	v_pk_add_f32 v[42:43], v[42:43], v[42:43] op_sel:[0,1] op_sel_hi:[1,0]
	v_pk_fma_f32 v[64:65], v[38:39], s[6:7], v[46:47] op_sel_hi:[1,0,1]
	v_pk_fma_f32 v[46:47], v[36:37], s[6:7], v[44:45] op_sel_hi:[1,0,1]
	v_pk_fma_f32 v[48:49], v[34:35], s[6:7], v[48:49] op_sel_hi:[1,0,1]
	v_add_f32_e32 v38, v64, v65
	v_add_f32_e32 v40, v62, v63
	v_mov_b32_e32 v133, v48
	v_mov_b32_e32 v43, v49
	v_mov_b32_e32 v39, v46
	v_mov_b32_e32 v41, v47
	v_pk_add_f32 v[34:35], v[132:133], v[42:43]
	v_pk_add_f32 v[36:37], v[38:39], v[40:41]
	s_mov_b32 s6, 0xf800000
	v_pk_add_f32 v[34:35], v[34:35], v[36:37]
	s_nop 0
	v_add_f32_e32 v34, v34, v35
	ds_bpermute_b32 v35, v252, v67
	s_waitcnt lgkmcnt(0)
	v_add_f32_e32 v35, v67, v35
	ds_bpermute_b32 v36, v243, v35
	s_waitcnt lgkmcnt(0)
	v_add_f32_e32 v35, v35, v36
	ds_bpermute_b32 v36, v244, v35
	s_waitcnt lgkmcnt(0)
	v_add_f32_e32 v35, v35, v36
	ds_bpermute_b32 v36, v245, v35
	s_waitcnt lgkmcnt(0)
	v_add_f32_e32 v35, v35, v36
	ds_bpermute_b32 v36, v246, v35
	s_waitcnt lgkmcnt(0)
	v_add_f32_e32 v35, v35, v36
	ds_bpermute_b32 v36, v247, v35
	s_waitcnt lgkmcnt(0)
	v_add_f32_e32 v42, v35, v36
	ds_bpermute_b32 v35, v252, v34
	v_fmamk_f32 v119, v42, 0xba800000, v119
	v_fmac_f32_e32 v118, 0xba800000, v42
	v_fmamk_f32 v117, v42, 0xba800000, v117
	v_fmac_f32_e32 v116, 0xba800000, v42
	s_waitcnt lgkmcnt(0)
	v_add_f32_e32 v34, v34, v35
	ds_bpermute_b32 v35, v243, v34
	v_pk_mul_f32 v[36:37], v[118:119], v[118:119]
	v_fmamk_f32 v109, v42, 0xba800000, v109
	v_fmac_f32_e32 v108, 0xba800000, v42
	v_fmamk_f32 v111, v42, 0xba800000, v111
	s_waitcnt lgkmcnt(0)
	v_add_f32_e32 v34, v34, v35
	ds_bpermute_b32 v35, v244, v34
	v_fmac_f32_e32 v110, 0xba800000, v42
	v_fmac_f32_e32 v60, 0xba800000, v42
	v_fmac_f32_e32 v58, 0xba800000, v42
	v_fmamk_f32 v61, v42, 0xba800000, v61
	s_waitcnt lgkmcnt(0)
	v_add_f32_e32 v34, v34, v35
	ds_bpermute_b32 v35, v245, v34
	v_fmamk_f32 v59, v42, 0xba800000, v59
	v_fmamk_f32 v53, v42, 0xba800000, v53
	v_fmac_f32_e32 v52, 0xba800000, v42
	v_fmamk_f32 v51, v42, 0xba800000, v51
	s_waitcnt lgkmcnt(0)
; __device__ __forceinline__ void ph_ln2(const Ctx& X, CArgs a, int l, int nrows) {
;     ...
;         for (int q = 0; q < 2; ++q) rstd[q] = 1.0f / sqrtf(wave_sum(s[q]) * (1.0f / D) + LN_EPS);
;         const float* md1 = (const float*)(X.ws + WS_MOD) + (size_t)(1 * 5 + (isc ? 4 : b)) * 6144;
; #pragma unroll
;         for (int j = 0; j < 4; ++j) { const int c = 4 * X.lane + 256 * j; const f32x4 g4 = *(const f32x4*)(lg + c), b4 = *(const f32x4*)(lb + c);
; #pragma unroll
;             for (int q = 0; q < 2; ++q) { const f32x4 y = v[q][j] * rstd[q] * g4 + b4;
;                 if (l == 0) { *(f32x4*)(X2 + (size_t)(r0 + q) * D + c) = y;
;                     const f32x4 h = y * (*(const f32x4*)(md1 + 1024 + c) + 1.0f) + *(const f32x4*)(md1 + c);
	v_add_f32_e32 v34, v34, v35
	ds_bpermute_b32 v35, v246, v34
	v_fmac_f32_e32 v50, 0xba800000, v42
	s_waitcnt lgkmcnt(0)
	v_add_f32_e32 v34, v34, v35
	ds_bpermute_b32 v35, v247, v34
	s_waitcnt lgkmcnt(0)
	v_add_f32_e32 v43, v34, v35
	v_pk_mul_f32 v[34:35], v[116:117], v[116:117]
	v_fmamk_f32 v121, v43, 0xba800000, v121
	v_pk_mov_b32 v[38:39], v[36:37], v[34:35] op_sel:[1,0]
	v_mov_b32_e32 v37, v35
	v_pk_add_f32 v[34:35], v[38:39], v[36:37]
	v_pk_mul_f32 v[36:37], v[108:109], v[108:109]
	v_pk_add_f32 v[34:35], v[34:35], v[34:35] op_sel_hi:[0,1]
	v_pk_mul_f32 v[38:39], v[110:111], v[110:111]
	v_mul_f32_e32 v34, v60, v60
	v_pk_mov_b32 v[40:41], v[38:39], v[36:37] op_sel:[1,0]
	v_mov_b32_e32 v39, v37
	v_pk_add_f32 v[36:37], v[40:41], v[38:39]
	v_pk_fma_f32 v[38:39], v[60:61], v[60:61], v[34:35] op_sel_hi:[1,1,0]
	v_mul_f32_e32 v34, v58, v58
	v_pk_add_f32 v[36:37], v[36:37], v[36:37] op_sel_hi:[0,1]
	v_pk_fma_f32 v[40:41], v[58:59], v[58:59], v[34:35] op_sel_hi:[1,1,0]
	v_mul_f32_e32 v38, v50, v50
	v_mul_f32_e32 v40, v51, v51
	v_mul_f32_e32 v34, v52, v52
	v_mul_f32_e32 v36, v53, v53
	v_pk_add_f32 v[38:39], v[38:39], v[40:41]
	v_pk_add_f32 v[34:35], v[34:35], v[36:37]
	v_fmamk_f32 v123, v43, 0xba800000, v123
	v_pk_add_f32 v[34:35], v[38:39], v[34:35]
	v_fmac_f32_e32 v120, 0xba800000, v43
	v_add_f32_e32 v34, v34, v35
	v_fmac_f32_e32 v122, 0xba800000, v43
	v_mul_f32_e32 v35, v123, v123
	v_mul_f32_e32 v36, v121, v121
	v_fmac_f32_e32 v35, v122, v122
	v_fmac_f32_e32 v36, v120, v120
	v_fmamk_f32 v113, v43, 0xba800000, v113
	v_fmamk_f32 v115, v43, 0xba800000, v115
	v_add_f32_e32 v35, v35, v36
	v_fmac_f32_e32 v112, 0xba800000, v43
	v_fmac_f32_e32 v114, 0xba800000, v43
	v_mul_f32_e32 v36, v115, v115
	v_mul_f32_e32 v37, v113, v113
	v_fmac_f32_e32 v36, v114, v114
	v_fmac_f32_e32 v37, v112, v112
	v_add_f32_e32 v36, v36, v37
	v_fmamk_f32 v63, v43, 0xba800000, v63
	v_fmamk_f32 v65, v43, 0xba800000, v65
	v_add_f32_e32 v35, v35, v36
	v_fmac_f32_e32 v62, 0xba800000, v43
	v_fmac_f32_e32 v64, 0xba800000, v43
	v_mul_f32_e32 v36, v65, v65
	v_mul_f32_e32 v37, v63, v63
	v_fmac_f32_e32 v36, v64, v64
	v_fmac_f32_e32 v37, v62, v62
	v_add_f32_e32 v36, v36, v37
	v_fmamk_f32 v47, v43, 0xba800000, v47
	v_fmamk_f32 v49, v43, 0xba800000, v49
	v_add_f32_e32 v35, v36, v35
	v_fmac_f32_e32 v46, 0xba800000, v43
	v_fmac_f32_e32 v48, 0xba800000, v43
	v_mul_f32_e32 v36, v49, v49
	v_mul_f32_e32 v37, v47, v47
	v_fmac_f32_e32 v36, v48, v48
	v_fmac_f32_e32 v37, v46, v46
	v_add_f32_e32 v36, v36, v37
	v_add_f32_e32 v35, v36, v35
	ds_bpermute_b32 v36, v252, v34
	s_waitcnt lgkmcnt(0)
	v_add_f32_e32 v34, v34, v36
	ds_bpermute_b32 v36, v243, v34
	s_waitcnt lgkmcnt(0)
	v_add_f32_e32 v34, v34, v36
	ds_bpermute_b32 v36, v244, v34
	s_waitcnt lgkmcnt(0)
	v_add_f32_e32 v34, v34, v36
	ds_bpermute_b32 v36, v245, v34
	s_waitcnt lgkmcnt(0)
	v_add_f32_e32 v34, v34, v36
	ds_bpermute_b32 v36, v246, v34
	s_waitcnt lgkmcnt(0)
	v_add_f32_e32 v34, v34, v36
	ds_bpermute_b32 v36, v247, v34
	s_waitcnt lgkmcnt(0)
	v_add_f32_e32 v34, v34, v36
	v_fmamk_f32 v34, v34, 0x3a800000, v239
	v_cmp_gt_f32_e32 vcc, s6, v34
	v_mul_f32_e32 v36, 0x4f800000, v34
	s_nop 0
	v_cndmask_b32_e32 v34, v34, v36, vcc
	v_sqrt_f32_e32 v36, v34
	s_nop 0
	v_add_u32_e32 v37, -1, v36
	v_fma_f32 v38, -v37, v36, v34
	v_cmp_ge_f32_e64 s[6:7], 0, v38
	v_add_u32_e32 v38, 1, v36
	s_nop 0
	v_cndmask_b32_e64 v37, v36, v37, s[6:7]
	v_fma_f32 v36, -v38, v36, v34
	v_cmp_lt_f32_e64 s[6:7], 0, v36
	s_nop 1
	v_cndmask_b32_e64 v36, v37, v38, s[6:7]
	v_mul_f32_e32 v37, 0x37800000, v36
	v_cndmask_b32_e32 v36, v36, v37, vcc
	v_cmp_class_f32_e32 vcc, v34, v238
	s_nop 1
	v_cndmask_b32_e32 v34, v36, v34, vcc
	v_div_scale_f32 v36, s[6:7], v34, v34, 1.0
	v_rcp_f32_e32 v37, v36
	s_lshl_b64 s[6:7], s[16:17], 2
	s_add_u32 s6, s31, s6
	s_addc_u32 s7, s33, s7
	v_fma_f32 v38, -v36, v37, 1.0
	v_fmac_f32_e32 v37, v38, v37
	v_div_scale_f32 v38, vcc, 1.0, v34, 1.0
	v_mul_f32_e32 v39, v38, v37
	v_fma_f32 v40, -v36, v39, v38
	v_fmac_f32_e32 v39, v40, v37
	v_fma_f32 v36, -v36, v39, v38
	v_div_fmas_f32 v36, v36, v37, v39
	v_div_fixup_f32 v54, v36, v34, 1.0
	ds_bpermute_b32 v34, v252, v35
	s_add_u32 s16, s6, 0x1000
	s_addc_u32 s17, s7, 0
	v_lshl_add_u64 v[206:207], s[16:17], 0, v[0:1]
	v_lshl_add_u64 v[208:209], s[6:7], 0, v[0:1]
	global_load_dwordx4 v[130:133], v[74:75], off
	global_load_dwordx4 v[154:157], v[76:77], off
	global_load_dwordx4 v[134:137], v[74:75], off offset:1024
	global_load_dwordx4 v[158:161], v[76:77], off offset:1024
	global_load_dwordx4 v[138:141], v[74:75], off offset:2048
	global_load_dwordx4 v[162:165], v[76:77], off offset:2048
	global_load_dwordx4 v[142:145], v[74:75], off offset:3072
	global_load_dwordx4 v[166:169], v[76:77], off offset:3072
	global_load_dwordx4 v[174:177], v[206:207], off
	global_load_dwordx4 v[190:193], v[208:209], off
	global_load_dwordx4 v[178:181], v[206:207], off offset:1024
	global_load_dwordx4 v[194:197], v[208:209], off offset:1024
	global_load_dwordx4 v[182:185], v[206:207], off offset:2048
	global_load_dwordx4 v[198:201], v[208:209], off offset:2048
	global_load_dwordx4 v[186:189], v[206:207], off offset:3072
	global_load_dwordx4 v[202:205], v[208:209], off offset:3072
	s_and_b64 vcc, exec, s[22:23]
	s_waitcnt lgkmcnt(0)
	v_add_f32_e32 v34, v35, v34
	ds_bpermute_b32 v35, v243, v34
	s_waitcnt lgkmcnt(0)
	v_add_f32_e32 v34, v34, v35
	ds_bpermute_b32 v35, v244, v34
	s_waitcnt lgkmcnt(0)
	v_add_f32_e32 v34, v34, v35
	ds_bpermute_b32 v35, v245, v34
	s_waitcnt lgkmcnt(0)
	v_add_f32_e32 v34, v34, v35
	ds_bpermute_b32 v35, v246, v34
	s_waitcnt lgkmcnt(0)
	v_add_f32_e32 v55, v34, v35
	s_waitcnt vmcnt(0)
	s_nop 1
	v_mov_b64_e32 v[34:35], v[130:131]
	v_mov_b64_e32 v[36:37], v[132:133]
	s_nop 1
	v_mov_b64_e32 v[38:39], v[154:155]
	v_mov_b64_e32 v[40:41], v[156:157]
	ds_bpermute_b32 v67, v247, v55
	v_pk_mul_f32 v[42:43], v[118:119], v[54:55] op_sel_hi:[1,0]
	v_pk_mul_f32 v[44:45], v[116:117], v[54:55] op_sel_hi:[1,0]
	v_pk_fma_f32 v[42:43], v[34:35], v[42:43], v[38:39]
	v_pk_fma_f32 v[44:45], v[36:37], v[44:45], v[40:41]
	s_cbranch_vccz .LBB0_2349
	s_load_dwordx2 s[18:19], s[12:13], 0xe0
	s_ashr_i32 s9, s8, 31
	s_lshl_b64 s[22:23], s[8:9], 12
	s_waitcnt lgkmcnt(0)
	s_add_u32 s18, s18, s22
	s_addc_u32 s19, s19, s23
	global_store_dwordx4 v0, v[42:45], s[18:19]
	s_mov_b64 s[18:19], 0
; __device__ __forceinline__ unsigned cvt_pk_bf16(float lo, float hi) { const f32x2_cv v = {lo, hi}; const bf16x2_cv b = __builtin_convertvector(v, bf16x2_cv); return __builtin_bit_cast(unsigned, b); }
; __device__ __forceinline__ unsigned pk_fp8x4(float a, float b, float c, float d) { int w = 0; w = __builtin_amdgcn_cvt_pk_fp8_f32(clamp448(a), clamp448(b), w, false); w = __builtin_amdgcn_cvt_pk_fp8_f32(clamp448(c), clamp448(d), w, true); return (unsigned)w; }
; __device__ __forceinline__ void ph_ln2(const Ctx& X, CArgs a, int l, int nrows) {
;     ...
;         for (int j = 0; j < 4; ++j) { const int c = 4 * X.lane + 256 * j; const f32x4 g4 = *(const f32x4*)(lg + c), b4 = *(const f32x4*)(lb + c);
; #pragma unroll
;             for (int q = 0; q < 2; ++q) { const f32x4 y = v[q][j] * rstd[q] * g4 + b4;
;                 if (l == 0) { *(f32x4*)(X2 + (size_t)(r0 + q) * D + c) = y;
;                     const f32x4 h = y * (*(const f32x4*)(md1 + 1024 + c) + 1.0f) + *(const f32x4*)(md1 + c);
;                     v2u wv; wv.x = cvt_pk_bf16(h[0], h[1]); wv.y = cvt_pk_bf16(h[2], h[3]); *(v2u*)(XH + (size_t)(r0 + q) * D + c) = wv;
;                     *(unsigned*)(X.ws + WS_XH8 + (size_t)(r0 + q) * D + c) = pg8::pk_fp8x4(h[0], h[1], h[2], h[3]); }
.LBB0_2349:
	v_lshl_add_u64 v[118:119], s[16:17], 0, v[0:1]
	s_andn2_b64 vcc, exec, s[18:19]
	v_lshl_add_u64 v[56:57], s[6:7], 0, v[0:1]
	s_cbranch_vccnz .LBB0_2351
	s_ashr_i32 s9, s8, 31
	s_lshl_b64 s[18:19], s[8:9], 12
	v_lshl_add_u64 v[116:117], v[78:79], 0, s[18:19]
	global_store_dwordx4 v[116:117], v[42:45], off
	s_nop 1
	v_mov_b64_e32 v[124:125], v[174:175]
	v_mov_b64_e32 v[126:127], v[176:177]
	v_mov_b32_e32 v103, v1
	s_lshl_b64 s[6:7], s[8:9], 10
	s_lshl_b64 s[18:19], s[8:9], 11
	v_pk_add_f32 v[116:117], v[126:127], 1.0 op_sel_hi:[1,0]
	v_pk_add_f32 v[128:129], v[124:125], 1.0 op_sel_hi:[1,0]
	s_nop 1
	v_mov_b64_e32 v[124:125], v[190:191]
	v_mov_b64_e32 v[126:127], v[192:193]
	v_pk_fma_f32 v[42:43], v[42:43], v[128:129], v[124:125]
	v_pk_fma_f32 v[44:45], v[44:45], v[116:117], v[126:127]
	v_cvt_pk_bf16_f32 v116, v42, v43
	v_med3_f32 v42, v42, s59, v250
	v_med3_f32 v43, v43, s59, v250
	v_cvt_pk_fp8_f32 v103, v42, v43
	v_med3_f32 v42, v44, s59, v250
	v_med3_f32 v43, v45, s59, v250
	v_cvt_pk_bf16_f32 v117, v44, v45
	v_cvt_pk_fp8_f32 v103, v42, v43 op_sel:[0,0,1]
	v_lshl_add_u64 v[124:125], v[80:81], 0, s[18:19]
	v_lshl_add_u64 v[42:43], v[82:83], 0, s[6:7]
	global_store_dwordx2 v[124:125], v[116:117], off
	global_store_dword v[42:43], v103, off

; __device__ __forceinline__ unsigned cvt_pk_bf16(float lo, float hi) { const f32x2_cv v = {lo, hi}; const bf16x2_cv b = __builtin_convertvector(v, bf16x2_cv); return __builtin_bit_cast(unsigned, b); }
; __device__ __forceinline__ unsigned pk_fp8x4(float a, float b, float c, float d) { int w = 0; w = __builtin_amdgcn_cvt_pk_fp8_f32(clamp448(a), clamp448(b), w, false); w = __builtin_amdgcn_cvt_pk_fp8_f32(clamp448(c), clamp448(d), w, true); return (unsigned)w; }
; __device__ __forceinline__ void ph_ln2(const Ctx& X, CArgs a, int l, int nrows) {
;     ...
;         for (int j = 0; j < 4; ++j) { const int c = 4 * X.lane + 256 * j; const f32x4 g4 = *(const f32x4*)(lg + c), b4 = *(const f32x4*)(lb + c);
; #pragma unroll
;             for (int q = 0; q < 2; ++q) { const f32x4 y = v[q][j] * rstd[q] * g4 + b4;
;                 if (l == 0) { *(f32x4*)(X2 + (size_t)(r0 + q) * D + c) = y;
;                     const f32x4 h = y * (*(const f32x4*)(md1 + 1024 + c) + 1.0f) + *(const f32x4*)(md1 + c);
;                     v2u wv; wv.x = cvt_pk_bf16(h[0], h[1]); wv.y = cvt_pk_bf16(h[2], h[3]); *(v2u*)(XH + (size_t)(r0 + q) * D + c) = wv;
;                     *(unsigned*)(X.ws + WS_XH8 + (size_t)(r0 + q) * D + c) = pg8::pk_fp8x4(h[0], h[1], h[2], h[3]); }
.LBB0_2353:
	s_andn2_b64 vcc, exec, s[18:19]
	s_cbranch_vccnz .LBB0_2355
	s_or_b32 s18, s8, 1
	s_ashr_i32 s19, s18, 31
	s_lshl_b64 s[24:25], s[18:19], 12
	v_lshl_add_u64 v[38:39], v[78:79], 0, s[24:25]
	global_store_dwordx4 v[38:39], v[34:37], off
	s_nop 1
	v_mov_b64_e32 v[38:39], v[174:175]
	v_mov_b64_e32 v[40:41], v[176:177]
	s_lshl_b64 s[22:23], s[18:19], 10
	s_lshl_b64 s[18:19], s[18:19], 11
	v_pk_add_f32 v[42:43], v[40:41], 1.0 op_sel_hi:[1,0]
	v_pk_add_f32 v[44:45], v[38:39], 1.0 op_sel_hi:[1,0]
	s_nop 1
	v_mov_b64_e32 v[38:39], v[190:191]
	v_mov_b64_e32 v[40:41], v[192:193]
	v_pk_fma_f32 v[36:37], v[36:37], v[42:43], v[40:41]
	v_pk_fma_f32 v[34:35], v[34:35], v[44:45], v[38:39]
	v_cvt_pk_bf16_f32 v39, v36, v37
	v_cvt_pk_bf16_f32 v38, v34, v35
	v_lshl_add_u64 v[40:41], v[80:81], 0, s[18:19]
	global_store_dwordx2 v[40:41], v[38:39], off
	v_med3_f32 v34, v34, s59, v250
	v_med3_f32 v35, v35, s59, v250
	v_mov_b32_e32 v38, v1
	v_cvt_pk_fp8_f32 v38, v34, v35
	v_med3_f32 v34, v36, s59, v250
	v_med3_f32 v35, v37, s59, v250
	v_cvt_pk_fp8_f32 v38, v34, v35 op_sel:[0,0,1]
	v_lshl_add_u64 v[34:35], v[82:83], 0, s[22:23]
	global_store_dword v[34:35], v38, off
.LBB0_2355:
	s_nop 1
	v_mov_b64_e32 v[34:35], v[134:135]
	v_mov_b64_e32 v[36:37], v[136:137]
	s_nop 0
	s_nop 1
	v_mov_b64_e32 v[38:39], v[158:159]
	v_mov_b64_e32 v[40:41], v[160:161]
	v_mov_b32_e32 v55, v54
	v_mov_b32_e32 v42, v54
	v_mov_b32_e32 v43, v54
	v_pk_mul_f32 v[42:43], v[108:109], v[42:43]
	v_pk_mul_f32 v[108:109], v[110:111], v[54:55]
	s_and_b64 vcc, exec, s[6:7]
	s_mov_b64 s[18:19], -1
	v_pk_fma_f32 v[44:45], v[42:43], v[36:37], v[40:41]
	v_pk_fma_f32 v[42:43], v[108:109], v[34:35], v[38:39]
	s_cbranch_vccnz .LBB0_2357
	s_load_dwordx2 s[18:19], s[12:13], 0xe0
	s_ashr_i32 s9, s8, 31
	s_lshl_b64 s[22:23], s[8:9], 12
	s_waitcnt lgkmcnt(0)
	s_add_u32 s18, s18, s22
	s_addc_u32 s19, s19, s23
	global_store_dwordx4 v0, v[42:45], s[18:19] offset:1024
	s_mov_b64 s[18:19], 0
.LBB0_2357:
	v_mov_b32_e32 v103, v1
	s_andn2_b64 vcc, exec, s[18:19]
	v_lshl_add_u64 v[108:109], s[16:17], 0, v[102:103]
	s_cbranch_vccnz .LBB0_2359
	s_ashr_i32 s9, s8, 31
	s_lshl_b64 s[22:23], s[8:9], 12
	v_lshl_add_u64 v[110:111], v[84:85], 0, s[22:23]
	global_store_dwordx4 v[110:111], v[42:45], off
	s_nop 1
	v_mov_b64_e32 v[118:119], v[178:179]
	v_mov_b64_e32 v[120:121], v[180:181]
	v_mov_b32_e32 v67, v1
	s_lshl_b64 s[18:19], s[8:9], 10
	s_lshl_b64 s[22:23], s[8:9], 11
	v_pk_add_f32 v[110:111], v[120:121], 1.0 op_sel_hi:[1,0]
	v_pk_add_f32 v[122:123], v[118:119], 1.0 op_sel_hi:[1,0]
	s_nop 1
	v_mov_b64_e32 v[118:119], v[194:195]
	v_mov_b64_e32 v[120:121], v[196:197]
	v_pk_fma_f32 v[42:43], v[42:43], v[122:123], v[118:119]
	v_pk_fma_f32 v[44:45], v[44:45], v[110:111], v[120:121]
	v_cvt_pk_bf16_f32 v110, v42, v43
	v_med3_f32 v42, v42, s59, v250
	v_med3_f32 v43, v43, s59, v250
	v_cvt_pk_fp8_f32 v67, v42, v43
	v_med3_f32 v42, v44, s59, v250
	v_med3_f32 v43, v45, s59, v250
	v_cvt_pk_bf16_f32 v111, v44, v45
	v_cvt_pk_fp8_f32 v67, v42, v43 op_sel:[0,0,1]
	v_lshl_add_u64 v[118:119], v[86:87], 0, s[22:23]
	v_lshl_add_u64 v[42:43], v[88:89], 0, s[18:19]
	global_store_dwordx2 v[118:119], v[110:111], off
	global_store_dword v[42:43], v67, off

; __device__ __forceinline__ unsigned cvt_pk_bf16(float lo, float hi) { const f32x2_cv v = {lo, hi}; const bf16x2_cv b = __builtin_convertvector(v, bf16x2_cv); return __builtin_bit_cast(unsigned, b); }
; __device__ __forceinline__ unsigned pk_fp8x4(float a, float b, float c, float d) { int w = 0; w = __builtin_amdgcn_cvt_pk_fp8_f32(clamp448(a), clamp448(b), w, false); w = __builtin_amdgcn_cvt_pk_fp8_f32(clamp448(c), clamp448(d), w, true); return (unsigned)w; }
; __device__ __forceinline__ void ph_ln2(const Ctx& X, CArgs a, int l, int nrows) {
;     ...
;         for (int j = 0; j < 4; ++j) { const int c = 4 * X.lane + 256 * j; const f32x4 g4 = *(const f32x4*)(lg + c), b4 = *(const f32x4*)(lb + c);
; #pragma unroll
;             for (int q = 0; q < 2; ++q) { const f32x4 y = v[q][j] * rstd[q] * g4 + b4;
;                 if (l == 0) { *(f32x4*)(X2 + (size_t)(r0 + q) * D + c) = y;
;                     const f32x4 h = y * (*(const f32x4*)(md1 + 1024 + c) + 1.0f) + *(const f32x4*)(md1 + c);
;                     v2u wv; wv.x = cvt_pk_bf16(h[0], h[1]); wv.y = cvt_pk_bf16(h[2], h[3]); *(v2u*)(XH + (size_t)(r0 + q) * D + c) = wv;
;                     *(unsigned*)(X.ws + WS_XH8 + (size_t)(r0 + q) * D + c) = pg8::pk_fp8x4(h[0], h[1], h[2], h[3]); }
.LBB0_2361:
	s_andn2_b64 vcc, exec, s[18:19]
	s_cbranch_vccnz .LBB0_2363
	s_or_b32 s18, s8, 1
	s_ashr_i32 s19, s18, 31
	s_lshl_b64 s[24:25], s[18:19], 12
	v_lshl_add_u64 v[38:39], v[84:85], 0, s[24:25]
	global_store_dwordx4 v[38:39], v[34:37], off
	s_nop 1
	v_mov_b64_e32 v[38:39], v[178:179]
	v_mov_b64_e32 v[40:41], v[180:181]
	s_lshl_b64 s[22:23], s[18:19], 10
	s_lshl_b64 s[18:19], s[18:19], 11
	v_pk_add_f32 v[42:43], v[40:41], 1.0 op_sel_hi:[1,0]
	v_pk_add_f32 v[44:45], v[38:39], 1.0 op_sel_hi:[1,0]
	s_nop 1
	v_mov_b64_e32 v[38:39], v[194:195]
	v_mov_b64_e32 v[40:41], v[196:197]
	v_pk_fma_f32 v[36:37], v[36:37], v[42:43], v[40:41]
	v_pk_fma_f32 v[34:35], v[34:35], v[44:45], v[38:39]
	v_cvt_pk_bf16_f32 v39, v36, v37
	v_cvt_pk_bf16_f32 v38, v34, v35
	v_lshl_add_u64 v[40:41], v[86:87], 0, s[18:19]
	global_store_dwordx2 v[40:41], v[38:39], off
	v_med3_f32 v34, v34, s59, v250
	v_med3_f32 v35, v35, s59, v250
	v_mov_b32_e32 v38, v1
	v_cvt_pk_fp8_f32 v38, v34, v35
	v_med3_f32 v34, v36, s59, v250
	v_med3_f32 v35, v37, s59, v250
	v_cvt_pk_fp8_f32 v38, v34, v35 op_sel:[0,0,1]
	v_lshl_add_u64 v[34:35], v[88:89], 0, s[22:23]
	global_store_dword v[34:35], v38, off
.LBB0_2363:
	s_nop 1
	v_mov_b64_e32 v[34:35], v[138:139]
	v_mov_b64_e32 v[36:37], v[140:141]
	s_nop 0
	s_nop 1
	v_mov_b64_e32 v[38:39], v[162:163]
	v_mov_b64_e32 v[40:41], v[164:165]
	v_mov_b32_e32 v42, v54
	v_mov_b32_e32 v43, v54
	v_pk_mul_f32 v[60:61], v[60:61], v[54:55]
	v_pk_mul_f32 v[42:43], v[58:59], v[42:43]
	s_and_b64 vcc, exec, s[6:7]
	s_mov_b64 s[18:19], -1
	v_pk_fma_f32 v[44:45], v[42:43], v[36:37], v[40:41]
	v_pk_fma_f32 v[42:43], v[60:61], v[34:35], v[38:39]
	s_cbranch_vccnz .LBB0_2365
	s_load_dwordx2 s[18:19], s[12:13], 0xe0
	s_ashr_i32 s9, s8, 31
	s_lshl_b64 s[22:23], s[8:9], 12
	s_waitcnt lgkmcnt(0)
	s_add_u32 s18, s18, s22
	s_addc_u32 s19, s19, s23
	global_store_dwordx4 v0, v[42:45], s[18:19] offset:2048
	s_mov_b64 s[18:19], 0
.LBB0_2365:
	v_mov_b32_e32 v105, v1
	s_andn2_b64 vcc, exec, s[18:19]
	v_lshl_add_u64 v[58:59], s[16:17], 0, v[104:105]
	s_cbranch_vccnz .LBB0_2367
	s_ashr_i32 s9, s8, 31
	s_lshl_b64 s[22:23], s[8:9], 12
	v_lshl_add_u64 v[60:61], v[90:91], 0, s[22:23]
	global_store_dwordx4 v[60:61], v[42:45], off
	s_nop 1
	v_mov_b64_e32 v[108:109], v[182:183]
	v_mov_b64_e32 v[110:111], v[184:185]
	s_lshl_b64 s[22:23], s[8:9], 11
	s_lshl_b64 s[18:19], s[8:9], 10
	v_pk_add_f32 v[60:61], v[110:111], 1.0 op_sel_hi:[1,0]
	v_pk_add_f32 v[112:113], v[108:109], 1.0 op_sel_hi:[1,0]
	s_nop 1
	v_mov_b64_e32 v[108:109], v[198:199]
	v_mov_b64_e32 v[110:111], v[200:201]
	v_pk_fma_f32 v[44:45], v[44:45], v[60:61], v[110:111]
	v_pk_fma_f32 v[42:43], v[42:43], v[112:113], v[108:109]
	v_cvt_pk_bf16_f32 v61, v44, v45
	v_cvt_pk_bf16_f32 v60, v42, v43
	v_lshl_add_u64 v[108:109], v[92:93], 0, s[22:23]
	global_store_dwordx2 v[108:109], v[60:61], off
	v_med3_f32 v42, v42, s59, v250
	v_med3_f32 v43, v43, s59, v250
	v_mov_b32_e32 v60, v1
	v_cvt_pk_fp8_f32 v60, v42, v43
	v_med3_f32 v42, v44, s59, v250
	v_med3_f32 v43, v45, s59, v250
	v_cvt_pk_fp8_f32 v60, v42, v43 op_sel:[0,0,1]
	v_lshl_add_u64 v[42:43], v[94:95], 0, s[18:19]
	global_store_dword v[42:43], v60, off

; __device__ __forceinline__ unsigned cvt_pk_bf16(float lo, float hi) { const f32x2_cv v = {lo, hi}; const bf16x2_cv b = __builtin_convertvector(v, bf16x2_cv); return __builtin_bit_cast(unsigned, b); }
; __device__ __forceinline__ unsigned pk_fp8x4(float a, float b, float c, float d) { int w = 0; w = __builtin_amdgcn_cvt_pk_fp8_f32(clamp448(a), clamp448(b), w, false); w = __builtin_amdgcn_cvt_pk_fp8_f32(clamp448(c), clamp448(d), w, true); return (unsigned)w; }
; __device__ __forceinline__ void ph_ln2(const Ctx& X, CArgs a, int l, int nrows) {
;     ...
;         for (int j = 0; j < 4; ++j) { const int c = 4 * X.lane + 256 * j; const f32x4 g4 = *(const f32x4*)(lg + c), b4 = *(const f32x4*)(lb + c);
; #pragma unroll
;             for (int q = 0; q < 2; ++q) { const f32x4 y = v[q][j] * rstd[q] * g4 + b4;
;                 if (l == 0) { *(f32x4*)(X2 + (size_t)(r0 + q) * D + c) = y;
;                     const f32x4 h = y * (*(const f32x4*)(md1 + 1024 + c) + 1.0f) + *(const f32x4*)(md1 + c);
;                     v2u wv; wv.x = cvt_pk_bf16(h[0], h[1]); wv.y = cvt_pk_bf16(h[2], h[3]); *(v2u*)(XH + (size_t)(r0 + q) * D + c) = wv;
;                     *(unsigned*)(X.ws + WS_XH8 + (size_t)(r0 + q) * D + c) = pg8::pk_fp8x4(h[0], h[1], h[2], h[3]); }
.LBB0_2369:
	s_andn2_b64 vcc, exec, s[18:19]
	s_cbranch_vccnz .LBB0_2371
	s_or_b32 s18, s8, 1
	s_ashr_i32 s19, s18, 31
	s_lshl_b64 s[24:25], s[18:19], 12
	v_lshl_add_u64 v[38:39], v[90:91], 0, s[24:25]
	global_store_dwordx4 v[38:39], v[34:37], off
	s_nop 1
	v_mov_b64_e32 v[38:39], v[182:183]
	v_mov_b64_e32 v[40:41], v[184:185]
	s_lshl_b64 s[22:23], s[18:19], 10
	s_lshl_b64 s[18:19], s[18:19], 11
	v_pk_add_f32 v[42:43], v[40:41], 1.0 op_sel_hi:[1,0]
	v_pk_add_f32 v[44:45], v[38:39], 1.0 op_sel_hi:[1,0]
	s_nop 1
	v_mov_b64_e32 v[38:39], v[198:199]
	v_mov_b64_e32 v[40:41], v[200:201]
	v_pk_fma_f32 v[36:37], v[36:37], v[42:43], v[40:41]
	v_pk_fma_f32 v[34:35], v[34:35], v[44:45], v[38:39]
	v_cvt_pk_bf16_f32 v39, v36, v37
	v_cvt_pk_bf16_f32 v38, v34, v35
	v_lshl_add_u64 v[40:41], v[92:93], 0, s[18:19]
	global_store_dwordx2 v[40:41], v[38:39], off
	v_med3_f32 v34, v34, s59, v250
	v_med3_f32 v35, v35, s59, v250
	v_mov_b32_e32 v38, v1
	v_cvt_pk_fp8_f32 v38, v34, v35
	v_med3_f32 v34, v36, s59, v250
	v_med3_f32 v35, v37, s59, v250
	v_cvt_pk_fp8_f32 v38, v34, v35 op_sel:[0,0,1]
	v_lshl_add_u64 v[34:35], v[94:95], 0, s[22:23]
	global_store_dword v[34:35], v38, off
.LBB0_2371:
	s_nop 1
	v_mov_b64_e32 v[34:35], v[142:143]
	v_mov_b64_e32 v[36:37], v[144:145]
	s_nop 0
	s_nop 1
	v_mov_b64_e32 v[38:39], v[166:167]
	v_mov_b64_e32 v[40:41], v[168:169]
	v_mov_b32_e32 v42, v54
	v_mov_b32_e32 v43, v54
	v_pk_mul_f32 v[50:51], v[50:51], v[54:55]
	v_pk_mul_f32 v[42:43], v[52:53], v[42:43]
	s_and_b64 vcc, exec, s[6:7]
	s_mov_b64 s[18:19], -1
	v_pk_fma_f32 v[44:45], v[42:43], v[36:37], v[40:41]
	v_pk_fma_f32 v[42:43], v[50:51], v[34:35], v[38:39]
	s_cbranch_vccnz .LBB0_2373
	s_load_dwordx2 s[18:19], s[12:13], 0xe0
	s_ashr_i32 s9, s8, 31
	s_lshl_b64 s[22:23], s[8:9], 12
	s_waitcnt lgkmcnt(0)
	s_add_u32 s18, s18, s22
	s_addc_u32 s19, s19, s23
	global_store_dwordx4 v0, v[42:45], s[18:19] offset:3072
	s_mov_b64 s[18:19], 0
.LBB0_2373:
	v_mov_b32_e32 v107, v1
	s_andn2_b64 vcc, exec, s[18:19]
	v_lshl_add_u64 v[50:51], s[16:17], 0, v[106:107]
	s_cbranch_vccnz .LBB0_2375
	s_ashr_i32 s9, s8, 31
	s_lshl_b64 s[18:19], s[8:9], 12
	v_lshl_add_u64 v[52:53], v[96:97], 0, s[18:19]
	global_store_dwordx4 v[52:53], v[42:45], off
	s_nop 1
	v_mov_b64_e32 v[52:53], v[186:187]
	v_mov_b64_e32 v[54:55], v[188:189]
	s_lshl_b64 s[18:19], s[8:9], 11
	s_lshl_b64 s[16:17], s[8:9], 10
	v_pk_add_f32 v[58:59], v[54:55], 1.0 op_sel_hi:[1,0]
	v_pk_add_f32 v[60:61], v[52:53], 1.0 op_sel_hi:[1,0]
	s_nop 1
	v_mov_b64_e32 v[52:53], v[202:203]
	v_mov_b64_e32 v[54:55], v[204:205]
	v_pk_fma_f32 v[44:45], v[44:45], v[58:59], v[54:55]
	v_pk_fma_f32 v[42:43], v[42:43], v[60:61], v[52:53]
	v_cvt_pk_bf16_f32 v53, v44, v45
	v_cvt_pk_bf16_f32 v52, v42, v43
	v_lshl_add_u64 v[54:55], v[98:99], 0, s[18:19]
	global_store_dwordx2 v[54:55], v[52:53], off
	v_med3_f32 v42, v42, s59, v250
	v_med3_f32 v43, v43, s59, v250
	v_mov_b32_e32 v52, v1
	v_cvt_pk_fp8_f32 v52, v42, v43
	v_med3_f32 v42, v44, s59, v250
	v_med3_f32 v43, v45, s59, v250
	v_cvt_pk_fp8_f32 v52, v42, v43 op_sel:[0,0,1]
	v_lshl_add_u64 v[42:43], v[100:101], 0, s[16:17]
	global_store_dword v[42:43], v52, off

; __device__ __forceinline__ unsigned cvt_pk_bf16(float lo, float hi) { const f32x2_cv v = {lo, hi}; const bf16x2_cv b = __builtin_convertvector(v, bf16x2_cv); return __builtin_bit_cast(unsigned, b); }
; __device__ __forceinline__ unsigned pk_fp8x4(float a, float b, float c, float d) { int w = 0; w = __builtin_amdgcn_cvt_pk_fp8_f32(clamp448(a), clamp448(b), w, false); w = __builtin_amdgcn_cvt_pk_fp8_f32(clamp448(c), clamp448(d), w, true); return (unsigned)w; }
; __device__ __forceinline__ void ph_ln2(const Ctx& X, CArgs a, int l, int nrows) {
;     ...
;         for (int j = 0; j < 4; ++j) { const int c = 4 * X.lane + 256 * j; const f32x4 g4 = *(const f32x4*)(lg + c), b4 = *(const f32x4*)(lb + c);
; #pragma unroll
;             for (int q = 0; q < 2; ++q) { const f32x4 y = v[q][j] * rstd[q] * g4 + b4;
;                 if (l == 0) { *(f32x4*)(X2 + (size_t)(r0 + q) * D + c) = y;
;                     const f32x4 h = y * (*(const f32x4*)(md1 + 1024 + c) + 1.0f) + *(const f32x4*)(md1 + c);
;                     v2u wv; wv.x = cvt_pk_bf16(h[0], h[1]); wv.y = cvt_pk_bf16(h[2], h[3]); *(v2u*)(XH + (size_t)(r0 + q) * D + c) = wv;
;                     *(unsigned*)(X.ws + WS_XH8 + (size_t)(r0 + q) * D + c) = pg8::pk_fp8x4(h[0], h[1], h[2], h[3]); }
.LBB0_2377:
	s_andn2_b64 vcc, exec, s[6:7]
	s_cbranch_vccnz .LBB0_2316
	s_or_b32 s6, s8, 1
	s_ashr_i32 s7, s6, 31
	s_lshl_b64 s[16:17], s[6:7], 12
	v_lshl_add_u64 v[38:39], v[96:97], 0, s[16:17]
	global_store_dwordx4 v[38:39], v[34:37], off
	s_nop 1
	v_mov_b64_e32 v[38:39], v[186:187]
	v_mov_b64_e32 v[40:41], v[188:189]
	s_lshl_b64 s[8:9], s[6:7], 10
	s_lshl_b64 s[6:7], s[6:7], 11
	v_pk_add_f32 v[42:43], v[40:41], 1.0 op_sel_hi:[1,0]
	v_pk_add_f32 v[44:45], v[38:39], 1.0 op_sel_hi:[1,0]
	s_nop 1
	v_mov_b64_e32 v[38:39], v[202:203]
	v_mov_b64_e32 v[40:41], v[204:205]
	v_pk_fma_f32 v[36:37], v[36:37], v[42:43], v[40:41]
	v_pk_fma_f32 v[34:35], v[34:35], v[44:45], v[38:39]
	v_cvt_pk_bf16_f32 v39, v36, v37
	v_cvt_pk_bf16_f32 v38, v34, v35
	v_lshl_add_u64 v[40:41], v[98:99], 0, s[6:7]
	global_store_dwordx2 v[40:41], v[38:39], off
	v_med3_f32 v0, v34, s59, v250
	v_med3_f32 v34, v35, s59, v250
	v_mov_b32_e32 v38, v1
	v_cvt_pk_fp8_f32 v38, v0, v34
	v_med3_f32 v0, v36, s59, v250
	v_med3_f32 v34, v37, s59, v250
	v_cvt_pk_fp8_f32 v38, v0, v34 op_sel:[0,0,1]
	v_lshl_add_u64 v[34:35], v[100:101], 0, s[8:9]
	global_store_dword v[34:35], v38, off
	s_branch .LBB0_2316
